# GLA3 row-norm wave sum: xor-1/2/4/8 butterfly steps via DPP adds instead of ds_bpermute (bit-identical); on top of late stagger barrier + xcd first barrier
# speedup vs baseline: 1.0005x; 1.0005x over previous
.LBB0_86:
	s_ashr_i32 s2, s6, 2
	s_ashr_i32 s3, s2, 31
	s_lshl_b64 s[4:5], s[2:3], 12
	s_mul_hi_i32 s8, s2, 0x3200
	s_mul_i32 s9, s2, 0x3200
	s_add_u32 s2, s60, s4
	s_addc_u32 s3, s61, s5
	s_and_b32 s10, s7, 0x600
	s_lshl_b32 s10, s10, 1
	s_add_u32 s2, s2, s10
	s_addc_u32 s3, s3, 0
	s_add_u32 s4, s28, s4
	s_addc_u32 s5, s29, s5
	s_add_u32 s4, s4, s10
	s_addc_u32 s5, s5, 0
	global_load_dwordx4 v[14:17], v80, s[4:5] nt
	s_add_u32 s4, s78, s9
	s_addc_u32 s5, s79, s8
	s_add_u32 s4, s4, s10
	s_addc_u32 s5, s5, 0
	v_lshl_add_u64 v[18:19], s[4:5], 0, v[80:81]
	v_add_co_u32_e32 v18, vcc, s13, v18
	s_add_i32 s6, s6, s11
	s_nop 0
	v_addc_co_u32_e32 v19, vcc, 0, v19, vcc
	global_load_dwordx4 v[18:21], v[18:19], off nt
	s_add_i32 s7, s7, s12
	s_cmp_gt_i32 s6, 0x1ffff
	s_waitcnt vmcnt(1)
	v_lshlrev_b32_e32 v26, 16, v14
	v_and_b32_e32 v27, 0xffff0000, v14
	v_lshlrev_b32_e32 v22, 16, v17
	v_and_b32_e32 v23, 0xffff0000, v17
	v_lshlrev_b32_e32 v24, 16, v16
	v_and_b32_e32 v25, 0xffff0000, v16
	v_lshlrev_b32_e32 v16, 16, v15
	v_and_b32_e32 v17, 0xffff0000, v15
	v_pk_mul_f32 v[32:33], v[26:27], v[26:27]
	v_pk_mul_f32 v[30:31], v[16:17], v[16:17]
	v_add_f32_e32 v32, v32, v33
	v_add_f32_e32 v30, v30, v32
	v_pk_mul_f32 v[28:29], v[24:25], v[24:25]
	v_add_f32_e32 v30, v31, v30
	v_add_f32_e32 v28, v28, v30
	v_pk_mul_f32 v[14:15], v[22:23], v[22:23]
	s_waitcnt vmcnt(0)
	v_lshlrev_b32_e32 v34, 16, v18
	v_and_b32_e32 v35, 0xffff0000, v18
	v_add_f32_e32 v18, v29, v28
	v_lshlrev_b32_e32 v30, 16, v21
	v_and_b32_e32 v31, 0xffff0000, v21
	v_lshlrev_b32_e32 v32, 16, v20
	v_and_b32_e32 v33, 0xffff0000, v20
	v_lshlrev_b32_e32 v20, 16, v19
	v_and_b32_e32 v21, 0xffff0000, v19
	v_add_f32_e32 v14, v14, v18
	v_mul_f32_e32 v19, 0xbfb8aa3b, v32
	v_mul_f32_e32 v28, 0xbfb8aa3b, v33
	v_mul_f32_e32 v29, 0xbfb8aa3b, v20
	v_mul_f32_e32 v36, 0xbfb8aa3b, v21
	v_mul_f32_e32 v37, 0xbfb8aa3b, v34
	v_mul_f32_e32 v38, 0xbfb8aa3b, v35
	v_mul_f32_e32 v18, 0xbfb8aa3b, v30
	v_mul_f32_e32 v39, 0xbfb8aa3b, v31
	v_add_f32_e32 v40, v15, v14
	v_exp_f32_e32 v19, v19
	v_exp_f32_e32 v28, v28
	v_exp_f32_e32 v29, v29
	v_exp_f32_e32 v36, v36
	v_exp_f32_e32 v37, v37
	v_exp_f32_e32 v38, v38
	v_exp_f32_e32 v14, v18
	v_exp_f32_e32 v15, v39
	v_add_f32_e32 v18, 1.0, v19
	v_add_f32_e32 v19, 1.0, v28
	v_add_f32_e32 v28, 1.0, v29
	v_add_f32_e32 v29, 1.0, v36
	v_add_f32_e32 v36, 1.0, v37
	v_add_f32_e32 v37, 1.0, v38
	v_add_f32_e32 v38, 1.0, v14
	v_rcp_f32_e32 v14, v18
	v_rcp_f32_e32 v18, v28
	v_rcp_f32_e32 v28, v36
	v_rcp_f32_e32 v36, v38
	s_nop 0
	v_add_f32_dpp v38, v40, v40 quad_perm:[1,0,3,2] row_mask:0xf bank_mask:0xf
	v_add_f32_e32 v41, 1.0, v15
	v_rcp_f32_e32 v15, v19
	v_add_f32_dpp v38, v38, v38 quad_perm:[2,3,0,1] row_mask:0xf bank_mask:0xf
	v_rcp_f32_e32 v19, v29
	v_rcp_f32_e32 v29, v37
	v_add_f32_dpp v38, v38, v38 row_half_mirror row_mask:0xf bank_mask:0xf
	v_rcp_f32_e32 v37, v41
	s_nop 0
	v_add_f32_dpp v38, v38, v38 row_mirror row_mask:0xf bank_mask:0xf
	s_nop 1
	ds_bpermute_b32 v39, v12, v38
	s_waitcnt lgkmcnt(0)
	v_add_f32_e32 v38, v38, v39
	ds_bpermute_b32 v39, v13, v38
	s_waitcnt lgkmcnt(0)
	v_add_f32_e32 v38, v38, v39
	v_fmamk_f32 v38, v38, 0x3b000000, v162
	v_mul_f32_e32 v39, 0x4b800000, v38
	v_cmp_gt_f32_e32 vcc, s59, v38
	s_nop 1
	v_cndmask_b32_e32 v38, v38, v39, vcc
	v_rsq_f32_e32 v38, v38
	s_nop 0
	v_mul_f32_e32 v39, 0x45800000, v38
	v_cndmask_b32_e32 v38, v38, v39, vcc
	v_pk_mul_f32 v[26:27], v[38:39], v[26:27] op_sel_hi:[0,1]
	v_pk_mul_f32 v[16:17], v[38:39], v[16:17] op_sel_hi:[0,1]
	v_pk_mul_f32 v[24:25], v[38:39], v[24:25] op_sel_hi:[0,1]
	v_pk_mul_f32 v[22:23], v[38:39], v[22:23] op_sel_hi:[0,1]
	v_pk_mul_f32 v[26:27], v[0:1], v[26:27]
	v_pk_mul_f32 v[16:17], v[2:3], v[16:17]
	v_pk_mul_f32 v[24:25], v[4:5], v[24:25]
	v_pk_mul_f32 v[22:23], v[6:7], v[22:23]
	v_pk_mul_f32 v[26:27], v[26:27], v[34:35]
	v_pk_mul_f32 v[16:17], v[16:17], v[20:21]
	v_pk_mul_f32 v[20:21], v[24:25], v[32:33]
	v_pk_mul_f32 v[22:23], v[22:23], v[30:31]
	v_pk_mul_f32 v[24:25], v[28:29], v[26:27]
	v_pk_mul_f32 v[16:17], v[18:19], v[16:17]
	v_pk_mul_f32 v[18:19], v[14:15], v[20:21]
	v_pk_mul_f32 v[20:21], v[36:37], v[22:23]
	v_cvt_pk_bf16_f32 v14, v24, v25
	v_cvt_pk_bf16_f32 v15, v16, v17
	v_cvt_pk_bf16_f32 v16, v18, v19
	v_cvt_pk_bf16_f32 v17, v20, v21
	global_store_dwordx4 v80, v[14:17], s[2:3]
	s_cbranch_scc0 .LBB0_86
	v_readlane_b32 s12, v238, 11
	v_readlane_b32 s22, v238, 21
	v_readlane_b32 s23, v238, 22
	v_readlane_b32 s22, v235, 44
	v_readlane_b32 s13, v238, 12
	v_readlane_b32 s14, v238, 13
	v_readlane_b32 s15, v238, 14
	v_readlane_b32 s16, v238, 15
	v_readlane_b32 s17, v238, 16
	v_readlane_b32 s18, v238, 17
	v_readlane_b32 s19, v238, 18
	v_readlane_b32 s20, v238, 19
	v_readlane_b32 s21, v238, 20
	v_readlane_b32 s24, v238, 23
	v_readlane_b32 s25, v238, 24
	v_readlane_b32 s26, v238, 25
	v_readlane_b32 s27, v238, 26
	v_readlane_b32 s23, v235, 45
